# P4 K loop: extra s_setprio yield point after every 8 MFMAs (loop body), on top of packed P4 epilogue
# speedup vs baseline: 1.0076x; 1.0076x over previous
; #define PG8_STAGE(bufoff, gbase, voff) do { _Pragma("unroll") for (int _i = 0; _i < 2; ++_i) \
;         __builtin_amdgcn_global_load_lds((const unsigned*)((const char*)(gbase) + (voff)[_i]), (PG8_LAS unsigned*)(lds + (bufoff) + ldsw + _i * 8192), 16, 0, 0); } while (0)
; #define PG8_LDA(dst, b, h) do { _Pragma("unroll") for (int m = 0; m < 4; ++m) _Pragma("unroll") for (int k = 0; k < 2; ++k) dst[m][k] = *(const PG8_LAS bf16x8*)(lds + PG8_SA(b, h) + aoff + m * 2048 + k * 1024); } while (0)
; #define PG8_LDB(dst, b, h) do { _Pragma("unroll") for (int n = 0; n < 2; ++n) _Pragma("unroll") for (int k = 0; k < 2; ++k) dst[n][k] = *(const PG8_LAS bf16x8*)(lds + PG8_SB(b, h) + boff + n * 2048 + k * 1024); } while (0)
; #define PG8_MMA(ai, bj, At, Bt) do { __builtin_amdgcn_s_setprio(1); _Pragma("unroll") for (int m = 0; m < 4; ++m) _Pragma("unroll") for (int n = 0; n < 2; ++n) _Pragma("unroll") for (int k = 0; k < 2; ++k) \
;         acc[ai][bj][m][n] = __builtin_amdgcn_mfma_f32_16x16x32_bf16(Bt[n][k], At[m][k], acc[ai][bj][m][n], 0, 0, 0); __builtin_amdgcn_s_setprio(0); } while (0)
; template <class Epi, class Sched, bool ALIGN_EPI = false, bool SP2 = false, bool ABLK = false>
; __device__ __forceinline__ void gemm_phase(PG8_LAS unsigned char* lds, const Gemm g, const Sched& S, const Epi& E) {
;     ...
;         for (int t = 0; t < nt; t += 2) {
;             if constexpr (Epi::MID) { if (t == nt / 2) E.mid(acc, cur, wr, wc, fr, fq); }
;             const bool last = (t == nt - 2);
;             const char* a1 = cA + (size_t)(t + 1) * kstepA;
;             const char* a2 = last ? nA : cA + (size_t)(t + 2) * kstepA; const char* b2 = last ? nB : cB + (size_t)(t + 2) * kstep;
;             const char* a3 = a2 + kstepA; const char* b3 = b2 + kstep;
;             if (last && has_next) S.a_ready(nxt);
;             if constexpr (SP2) {
;             PG8_LDB(B0, 0, 0); PG8_LDB(B1, 0, 1); PG8_SCHED; PG8_LDA(At, 0, 0); PG8_STAGE(PG8_SA(1, 1), a1 + hstepA, voffA);
;             PG8_WAIT_V(8); PG8_WAIT_L(0); PG8_BAR; PG8_MMA(0, 0, At, B0); PG8_MMA(0, 1, At, B1); PG8_BAR; PG8_SCHED;
;             PG8_LDA(At, 0, 1); PG8_STAGE(PG8_SB(0, 0), b2, voffB); PG8_STAGE(PG8_SB(0, 1), b2 + hstep, voffB); PG8_STAGE(PG8_SA(0, 0), a2, voffA);
;             PG8_WAIT_V(8); PG8_WAIT_L(0); PG8_BAR; PG8_MMA(1, 0, At, B0); PG8_MMA(1, 1, At, B1); PG8_BAR; PG8_SCHED;
.LBB0_534:
	ds_read_b128 v[128:131], v143
	ds_read_b128 v[176:179], v143 offset:1024
	ds_read_b128 v[180:183], v143 offset:2048
	ds_read_b128 v[184:187], v143 offset:3072
	ds_read_b128 v[188:191], v167
	ds_read_b128 v[192:195], v167 offset:1024
	ds_read_b128 v[196:199], v167 offset:2048
	ds_read_b128 v[200:203], v167 offset:3072
	s_add_u32 s2, s8, 0x4000
	s_addc_u32 s34, s9, 0
	s_cmp_eq_u32 s63, 12
	s_cselect_b32 s38, s21, s2
	s_cselect_b32 s39, s7, s34
	s_cselect_b32 s36, s31, s61
	s_cselect_b32 s37, s23, s62
	s_add_u32 s34, s38, 0x8000
	s_addc_u32 s35, s39, 0
	s_mov_b32 m0, s58
	v_lshl_add_u64 v[172:173], s[8:9], 0, v[162:163]
	ds_read_b128 v[204:207], v168
	ds_read_b128 v[208:211], v168 offset:1024
	ds_read_b128 v[212:215], v168 offset:2048
	ds_read_b128 v[216:219], v168 offset:3072
	ds_read_b128 v[220:223], v168 offset:4096
	ds_read_b128 v[224:227], v168 offset:5120
	ds_read_b128 v[228:231], v168 offset:6144
	ds_read_b128 v[232:235], v168 offset:7168
	global_load_lds_dwordx4 v[172:173], off
	v_lshl_add_u64 v[172:173], s[8:9], 0, v[164:165]
	s_mov_b32 m0, s59
	s_nop 0
	global_load_lds_dwordx4 v[172:173], off
	s_waitcnt vmcnt(8)
	s_waitcnt lgkmcnt(0)
	s_barrier
	s_setprio 1
	s_waitcnt lgkmcnt(0)
	v_mfma_f32_16x16x32_bf16 v[124:127], v[128:131], v[204:207], v[124:127]
	v_mfma_f32_16x16x32_bf16 v[120:123], v[180:183], v[204:207], v[120:123]
	v_mfma_f32_16x16x32_bf16 v[108:111], v[128:131], v[212:215], v[108:111]
	v_mfma_f32_16x16x32_bf16 v[104:107], v[180:183], v[212:215], v[104:107]
	v_mfma_f32_16x16x32_bf16 v[92:95], v[128:131], v[220:223], v[92:95]
	v_mfma_f32_16x16x32_bf16 v[88:91], v[180:183], v[220:223], v[88:91]
	v_mfma_f32_16x16x32_bf16 v[76:79], v[128:131], v[228:231], v[76:79]
	v_mfma_f32_16x16x32_bf16 v[72:75], v[180:183], v[228:231], v[72:75]
	s_setprio 0
	s_setprio 1
	v_mfma_f32_16x16x32_bf16 v[124:127], v[176:179], v[208:211], v[124:127]
	v_mfma_f32_16x16x32_bf16 v[120:123], v[184:187], v[208:211], v[120:123]
	v_mfma_f32_16x16x32_bf16 v[108:111], v[176:179], v[216:219], v[108:111]
	v_mfma_f32_16x16x32_bf16 v[104:107], v[184:187], v[216:219], v[104:107]
	v_mfma_f32_16x16x32_bf16 v[92:95], v[176:179], v[224:227], v[92:95]
	v_mfma_f32_16x16x32_bf16 v[88:91], v[184:187], v[224:227], v[88:91]
	v_mfma_f32_16x16x32_bf16 v[76:79], v[176:179], v[232:235], v[76:79]
	v_mfma_f32_16x16x32_bf16 v[72:75], v[184:187], v[232:235], v[72:75]
	s_setprio 0
	s_setprio 1
	v_mfma_f32_16x16x32_bf16 v[116:119], v[188:191], v[204:207], v[116:119]
	v_mfma_f32_16x16x32_bf16 v[112:115], v[196:199], v[204:207], v[112:115]
	v_mfma_f32_16x16x32_bf16 v[100:103], v[188:191], v[212:215], v[100:103]
	v_mfma_f32_16x16x32_bf16 v[96:99], v[196:199], v[212:215], v[96:99]
	v_mfma_f32_16x16x32_bf16 v[84:87], v[188:191], v[220:223], v[84:87]
	v_mfma_f32_16x16x32_bf16 v[80:83], v[196:199], v[220:223], v[80:83]
	v_mfma_f32_16x16x32_bf16 v[68:71], v[188:191], v[228:231], v[68:71]
	v_mfma_f32_16x16x32_bf16 v[64:67], v[196:199], v[228:231], v[64:67]
	s_setprio 0
	s_setprio 1
	v_mfma_f32_16x16x32_bf16 v[116:119], v[192:195], v[208:211], v[116:119]
	v_mfma_f32_16x16x32_bf16 v[112:115], v[200:203], v[208:211], v[112:115]
	v_mfma_f32_16x16x32_bf16 v[100:103], v[192:195], v[216:219], v[100:103]
	v_mfma_f32_16x16x32_bf16 v[96:99], v[200:203], v[216:219], v[96:99]
	v_mfma_f32_16x16x32_bf16 v[84:87], v[192:195], v[224:227], v[84:87]
	v_mfma_f32_16x16x32_bf16 v[80:83], v[200:203], v[224:227], v[80:83]
	v_mfma_f32_16x16x32_bf16 v[68:71], v[192:195], v[232:235], v[68:71]
	v_mfma_f32_16x16x32_bf16 v[64:67], v[200:203], v[232:235], v[64:67]
	s_setprio 0
	s_barrier
	s_mov_b32 m0, s60
	v_lshl_add_u64 v[172:173], s[36:37], 0, v[136:137]
	ds_read_b128 v[204:207], v168 offset:16384
	ds_read_b128 v[208:211], v168 offset:17408
	ds_read_b128 v[212:215], v168 offset:18432
	ds_read_b128 v[216:219], v168 offset:19456
	ds_read_b128 v[220:223], v168 offset:20480
	ds_read_b128 v[224:227], v168 offset:21504
	ds_read_b128 v[228:231], v168 offset:22528
	ds_read_b128 v[232:235], v168 offset:23552
	global_load_lds_dwordx4 v[172:173], off
	s_add_i32 m0, s60, 0x2000
	s_add_u32 s70, s36, 0x40000
	v_lshl_add_u64 v[236:237], s[36:37], 0, v[132:133]
	s_addc_u32 s71, s37, 0
	s_add_i32 s2, s57, s3
	global_load_lds_dwordx4 v[236:237], off
	v_lshl_add_u64 v[238:239], s[70:71], 0, v[136:137]
	s_mov_b32 m0, s2
	s_nop 0
	global_load_lds_dwordx4 v[238:239], off
	v_lshl_add_u64 v[238:239], s[70:71], 0, v[132:133]
	s_add_i32 m0, s2, 0x2000
	s_nop 0
	global_load_lds_dwordx4 v[238:239], off
	v_lshl_add_u64 v[238:239], s[38:39], 0, v[138:139]
	s_mov_b32 m0, s40
	s_nop 0
	global_load_lds_dwordx4 v[238:239], off
	v_lshl_add_u64 v[238:239], s[38:39], 0, v[134:135]
	s_mov_b32 m0, s41
	s_nop 0
	global_load_lds_dwordx4 v[238:239], off
	s_waitcnt vmcnt(8)
	s_waitcnt lgkmcnt(0)
	s_barrier
; #define PG8_STAGE(bufoff, gbase, voff) do { _Pragma("unroll") for (int _i = 0; _i < 2; ++_i) \
;         __builtin_amdgcn_global_load_lds((const unsigned*)((const char*)(gbase) + (voff)[_i]), (PG8_LAS unsigned*)(lds + (bufoff) + ldsw + _i * 8192), 16, 0, 0); } while (0)
; #define PG8_LDA(dst, b, h) do { _Pragma("unroll") for (int m = 0; m < 4; ++m) _Pragma("unroll") for (int k = 0; k < 2; ++k) dst[m][k] = *(const PG8_LAS bf16x8*)(lds + PG8_SA(b, h) + aoff + m * 2048 + k * 1024); } while (0)
; #define PG8_LDB(dst, b, h) do { _Pragma("unroll") for (int n = 0; n < 2; ++n) _Pragma("unroll") for (int k = 0; k < 2; ++k) dst[n][k] = *(const PG8_LAS bf16x8*)(lds + PG8_SB(b, h) + boff + n * 2048 + k * 1024); } while (0)
; #define PG8_MMA(ai, bj, At, Bt) do { __builtin_amdgcn_s_setprio(1); _Pragma("unroll") for (int m = 0; m < 4; ++m) _Pragma("unroll") for (int n = 0; n < 2; ++n) _Pragma("unroll") for (int k = 0; k < 2; ++k) \
;         acc[ai][bj][m][n] = __builtin_amdgcn_mfma_f32_16x16x32_bf16(Bt[n][k], At[m][k], acc[ai][bj][m][n], 0, 0, 0); __builtin_amdgcn_s_setprio(0); } while (0)
; #define PG8_WAIT_V(n) asm volatile("s_waitcnt vmcnt(" #n ")" ::: "memory")
; #define PG8_WAIT_L(n) asm volatile("s_waitcnt lgkmcnt(" #n ")" ::: "memory")
; #define PG8_BAR __builtin_amdgcn_s_barrier()
; #define PG8_SCHED __builtin_amdgcn_sched_barrier(0)
; template <class Epi, class Sched, bool ALIGN_EPI = false, bool SP2 = false, bool ABLK = false>
; __device__ __forceinline__ void gemm_phase(PG8_LAS unsigned char* lds, const Gemm g, const Sched& S, const Epi& E) {
;     ...
;             PG8_WAIT_V(8); PG8_WAIT_L(0); PG8_BAR; PG8_MMA(1, 0, At, B0); PG8_MMA(1, 1, At, B1); PG8_BAR; PG8_SCHED;
;             PG8_LDB(B0, 1, 0); PG8_LDB(B1, 1, 1); PG8_SCHED; PG8_LDA(At, 1, 0); PG8_STAGE(PG8_SA(0, 1), a2 + hstepA, voffA);
;             PG8_WAIT_V(8); PG8_WAIT_L(0); PG8_BAR; PG8_MMA(0, 0, At, B0); PG8_MMA(0, 1, At, B1); PG8_BAR; PG8_SCHED;
	s_setprio 1
	s_waitcnt lgkmcnt(0)
	v_mfma_f32_16x16x32_bf16 v[60:63], v[128:131], v[204:207], v[60:63]
	v_mfma_f32_16x16x32_bf16 v[56:59], v[180:183], v[204:207], v[56:59]
	v_mfma_f32_16x16x32_bf16 v[44:47], v[128:131], v[212:215], v[44:47]
	v_mfma_f32_16x16x32_bf16 v[40:43], v[180:183], v[212:215], v[40:43]
	v_mfma_f32_16x16x32_bf16 v[28:31], v[128:131], v[220:223], v[28:31]
	v_mfma_f32_16x16x32_bf16 v[24:27], v[180:183], v[220:223], v[24:27]
	v_mfma_f32_16x16x32_bf16 v[12:15], v[128:131], v[228:231], v[12:15]
	v_mfma_f32_16x16x32_bf16 v[8:11], v[180:183], v[228:231], v[8:11]
	s_setprio 0
	s_setprio 1
	v_mfma_f32_16x16x32_bf16 v[60:63], v[176:179], v[208:211], v[60:63]
	v_mfma_f32_16x16x32_bf16 v[56:59], v[184:187], v[208:211], v[56:59]
	v_mfma_f32_16x16x32_bf16 v[44:47], v[176:179], v[216:219], v[44:47]
	v_mfma_f32_16x16x32_bf16 v[40:43], v[184:187], v[216:219], v[40:43]
	v_mfma_f32_16x16x32_bf16 v[28:31], v[176:179], v[224:227], v[28:31]
	v_mfma_f32_16x16x32_bf16 v[24:27], v[184:187], v[224:227], v[24:27]
	v_mfma_f32_16x16x32_bf16 v[12:15], v[176:179], v[232:235], v[12:15]
	v_mfma_f32_16x16x32_bf16 v[8:11], v[184:187], v[232:235], v[8:11]
	s_setprio 0
	s_setprio 1
	v_mfma_f32_16x16x32_bf16 v[52:55], v[188:191], v[204:207], v[52:55]
	v_mfma_f32_16x16x32_bf16 v[48:51], v[196:199], v[204:207], v[48:51]
	v_mfma_f32_16x16x32_bf16 v[36:39], v[188:191], v[212:215], v[36:39]
	v_mfma_f32_16x16x32_bf16 v[32:35], v[196:199], v[212:215], v[32:35]
	v_mfma_f32_16x16x32_bf16 v[20:23], v[188:191], v[220:223], v[20:23]
	v_mfma_f32_16x16x32_bf16 v[16:19], v[196:199], v[220:223], v[16:19]
	v_mfma_f32_16x16x32_bf16 v[4:7], v[188:191], v[228:231], v[4:7]
	v_mfma_f32_16x16x32_bf16 v[0:3], v[196:199], v[228:231], v[0:3]
	s_setprio 0
	s_setprio 1
	v_mfma_f32_16x16x32_bf16 v[52:55], v[192:195], v[208:211], v[52:55]
	v_mfma_f32_16x16x32_bf16 v[48:51], v[200:203], v[208:211], v[48:51]
	v_mfma_f32_16x16x32_bf16 v[36:39], v[192:195], v[216:219], v[36:39]
	v_mfma_f32_16x16x32_bf16 v[32:35], v[200:203], v[216:219], v[32:35]
	v_mfma_f32_16x16x32_bf16 v[20:23], v[192:195], v[224:227], v[20:23]
	v_mfma_f32_16x16x32_bf16 v[16:19], v[200:203], v[224:227], v[16:19]
	v_mfma_f32_16x16x32_bf16 v[4:7], v[192:195], v[232:235], v[4:7]
	v_mfma_f32_16x16x32_bf16 v[0:3], v[200:203], v[232:235], v[0:3]
	s_setprio 0
	s_barrier
	s_add_i32 s2, 0, 0x18000
	v_add_u32_e32 v171, s2, v166
	s_add_i32 s70, 0, 0x1c000
	ds_read_b128 v[128:131], v171
	ds_read_b128 v[176:179], v171 offset:1024
	ds_read_b128 v[180:183], v171 offset:2048
	ds_read_b128 v[184:187], v171 offset:3072
	v_add_u32_e32 v171, s70, v166
	ds_read_b128 v[188:191], v171
	ds_read_b128 v[192:195], v171 offset:1024
	ds_read_b128 v[196:199], v171 offset:2048
	ds_read_b128 v[200:203], v171 offset:3072
	s_add_u32 s38, s38, 0x4000
	s_addc_u32 s39, s39, 0
	s_mov_b32 m0, s44
	v_lshl_add_u64 v[238:239], s[38:39], 0, v[138:139]
	ds_read_b128 v[204:207], v168 offset:32768
	ds_read_b128 v[208:211], v168 offset:33792
	ds_read_b128 v[212:215], v168 offset:34816
	ds_read_b128 v[216:219], v168 offset:35840
	ds_read_b128 v[220:223], v168 offset:36864
	ds_read_b128 v[224:227], v168 offset:37888
	ds_read_b128 v[228:231], v168 offset:38912
	ds_read_b128 v[232:235], v168 offset:39936
	global_load_lds_dwordx4 v[238:239], off
	v_lshl_add_u64 v[238:239], s[38:39], 0, v[134:135]
	s_mov_b32 m0, s45
	s_nop 0
	global_load_lds_dwordx4 v[238:239], off
	s_waitcnt vmcnt(8)
	s_waitcnt lgkmcnt(0)
	s_barrier
	s_setprio 1
	s_waitcnt lgkmcnt(0)
	v_mfma_f32_16x16x32_bf16 v[124:127], v[128:131], v[204:207], v[124:127]
	v_mfma_f32_16x16x32_bf16 v[120:123], v[180:183], v[204:207], v[120:123]
	v_mfma_f32_16x16x32_bf16 v[108:111], v[128:131], v[212:215], v[108:111]
	v_mfma_f32_16x16x32_bf16 v[104:107], v[180:183], v[212:215], v[104:107]
	v_mfma_f32_16x16x32_bf16 v[92:95], v[128:131], v[220:223], v[92:95]
	v_mfma_f32_16x16x32_bf16 v[88:91], v[180:183], v[220:223], v[88:91]
	v_mfma_f32_16x16x32_bf16 v[76:79], v[128:131], v[228:231], v[76:79]
	v_mfma_f32_16x16x32_bf16 v[72:75], v[180:183], v[228:231], v[72:75]
	s_setprio 0
	s_setprio 1
	v_mfma_f32_16x16x32_bf16 v[124:127], v[176:179], v[208:211], v[124:127]
	v_mfma_f32_16x16x32_bf16 v[120:123], v[184:187], v[208:211], v[120:123]
	v_mfma_f32_16x16x32_bf16 v[108:111], v[176:179], v[216:219], v[108:111]
	v_mfma_f32_16x16x32_bf16 v[104:107], v[184:187], v[216:219], v[104:107]
	v_mfma_f32_16x16x32_bf16 v[92:95], v[176:179], v[224:227], v[92:95]
	v_mfma_f32_16x16x32_bf16 v[88:91], v[184:187], v[224:227], v[88:91]
	v_mfma_f32_16x16x32_bf16 v[76:79], v[176:179], v[232:235], v[76:79]
	v_mfma_f32_16x16x32_bf16 v[72:75], v[184:187], v[232:235], v[72:75]
	s_setprio 0
	s_setprio 1
	v_mfma_f32_16x16x32_bf16 v[116:119], v[188:191], v[204:207], v[116:119]
	v_mfma_f32_16x16x32_bf16 v[112:115], v[196:199], v[204:207], v[112:115]
	v_mfma_f32_16x16x32_bf16 v[100:103], v[188:191], v[212:215], v[100:103]
	v_mfma_f32_16x16x32_bf16 v[96:99], v[196:199], v[212:215], v[96:99]
	v_mfma_f32_16x16x32_bf16 v[84:87], v[188:191], v[220:223], v[84:87]
	v_mfma_f32_16x16x32_bf16 v[80:83], v[196:199], v[220:223], v[80:83]
	v_mfma_f32_16x16x32_bf16 v[68:71], v[188:191], v[228:231], v[68:71]
	v_mfma_f32_16x16x32_bf16 v[64:67], v[196:199], v[228:231], v[64:67]
	s_setprio 0
	s_setprio 1
	v_mfma_f32_16x16x32_bf16 v[116:119], v[192:195], v[208:211], v[116:119]
	v_mfma_f32_16x16x32_bf16 v[112:115], v[200:203], v[208:211], v[112:115]
	v_mfma_f32_16x16x32_bf16 v[100:103], v[192:195], v[216:219], v[100:103]
	v_mfma_f32_16x16x32_bf16 v[96:99], v[200:203], v[216:219], v[96:99]
	v_mfma_f32_16x16x32_bf16 v[84:87], v[192:195], v[224:227], v[84:87]
	v_mfma_f32_16x16x32_bf16 v[80:83], v[200:203], v[224:227], v[80:83]
	v_mfma_f32_16x16x32_bf16 v[68:71], v[192:195], v[232:235], v[68:71]
	v_mfma_f32_16x16x32_bf16 v[64:67], v[200:203], v[232:235], v[64:67]
	s_setprio 0
	s_barrier
; #define PG8_STAGE(bufoff, gbase, voff) do { _Pragma("unroll") for (int _i = 0; _i < 2; ++_i) \
;         __builtin_amdgcn_global_load_lds((const unsigned*)((const char*)(gbase) + (voff)[_i]), (PG8_LAS unsigned*)(lds + (bufoff) + ldsw + _i * 8192), 16, 0, 0); } while (0)
; #define PG8_LDA(dst, b, h) do { _Pragma("unroll") for (int m = 0; m < 4; ++m) _Pragma("unroll") for (int k = 0; k < 2; ++k) dst[m][k] = *(const PG8_LAS bf16x8*)(lds + PG8_SA(b, h) + aoff + m * 2048 + k * 1024); } while (0)
; #define PG8_MMA(ai, bj, At, Bt) do { __builtin_amdgcn_s_setprio(1); _Pragma("unroll") for (int m = 0; m < 4; ++m) _Pragma("unroll") for (int n = 0; n < 2; ++n) _Pragma("unroll") for (int k = 0; k < 2; ++k) \
;         acc[ai][bj][m][n] = __builtin_amdgcn_mfma_f32_16x16x32_bf16(Bt[n][k], At[m][k], acc[ai][bj][m][n], 0, 0, 0); __builtin_amdgcn_s_setprio(0); } while (0)
; #define PG8_WAIT_V(n) asm volatile("s_waitcnt vmcnt(" #n ")" ::: "memory")
; #define PG8_WAIT_L(n) asm volatile("s_waitcnt lgkmcnt(" #n ")" ::: "memory")
; #define PG8_BAR __builtin_amdgcn_s_barrier()
; #define PG8_SCHED __builtin_amdgcn_sched_barrier(0)
; template <class Epi, class Sched, bool ALIGN_EPI = false, bool SP2 = false, bool ABLK = false>
; __device__ __forceinline__ void gemm_phase(PG8_LAS unsigned char* lds, const Gemm g, const Sched& S, const Epi& E) {
;     ...
;             PG8_LDA(At, 1, 1); PG8_STAGE(PG8_SB(1, 0), b3, voffB); PG8_STAGE(PG8_SB(1, 1), b3 + hstep, voffB); PG8_STAGE(PG8_SA(1, 0), a3, voffA);
;             PG8_WAIT_V(8); PG8_WAIT_L(0); PG8_BAR; PG8_MMA(1, 0, At, B0); PG8_MMA(1, 1, At, B1); PG8_BAR; PG8_SCHED;
	s_add_i32 s2, s2, s3
	v_lshl_add_u64 v[172:173], v[172:173], 0, s[16:17]
	s_mov_b32 m0, s2
	ds_read_b128 v[204:207], v168 offset:49152
	ds_read_b128 v[208:211], v168 offset:50176
	ds_read_b128 v[212:215], v168 offset:51200
	ds_read_b128 v[216:219], v168 offset:52224
	ds_read_b128 v[220:223], v168 offset:53248
	ds_read_b128 v[224:227], v168 offset:54272
	ds_read_b128 v[228:231], v168 offset:55296
	ds_read_b128 v[232:235], v168 offset:56320
	global_load_lds_dwordx4 v[172:173], off
	s_add_i32 m0, s2, 0x2000
	s_add_u32 s36, s36, 0x40080
	v_lshl_add_u64 v[172:173], v[236:237], 0, s[16:17]
	s_addc_u32 s37, s37, 0
	s_add_i32 s2, s70, s3
	global_load_lds_dwordx4 v[172:173], off
	v_lshl_add_u64 v[172:173], s[36:37], 0, v[136:137]
	s_mov_b32 m0, s2
	s_nop 0
	global_load_lds_dwordx4 v[172:173], off
	v_lshl_add_u64 v[172:173], s[36:37], 0, v[132:133]
	s_add_i32 m0, s2, 0x2000
	s_nop 0
	global_load_lds_dwordx4 v[172:173], off
	v_lshl_add_u64 v[172:173], s[34:35], 0, v[138:139]
	s_mov_b32 m0, s55
	s_nop 0
	global_load_lds_dwordx4 v[172:173], off
	v_lshl_add_u64 v[172:173], s[34:35], 0, v[134:135]
	s_mov_b32 m0, s56
	s_nop 0
	global_load_lds_dwordx4 v[172:173], off
	s_waitcnt vmcnt(8)
	s_waitcnt lgkmcnt(0)
	s_barrier
	s_setprio 1
	s_waitcnt lgkmcnt(0)
	v_mfma_f32_16x16x32_bf16 v[60:63], v[128:131], v[204:207], v[60:63]
	v_mfma_f32_16x16x32_bf16 v[56:59], v[180:183], v[204:207], v[56:59]
	v_mfma_f32_16x16x32_bf16 v[44:47], v[128:131], v[212:215], v[44:47]
	v_mfma_f32_16x16x32_bf16 v[40:43], v[180:183], v[212:215], v[40:43]
	v_mfma_f32_16x16x32_bf16 v[28:31], v[128:131], v[220:223], v[28:31]
	v_mfma_f32_16x16x32_bf16 v[24:27], v[180:183], v[220:223], v[24:27]
	v_mfma_f32_16x16x32_bf16 v[12:15], v[128:131], v[228:231], v[12:15]
	v_mfma_f32_16x16x32_bf16 v[8:11], v[180:183], v[228:231], v[8:11]
	s_setprio 0
	s_setprio 1
	v_mfma_f32_16x16x32_bf16 v[60:63], v[176:179], v[208:211], v[60:63]
	v_mfma_f32_16x16x32_bf16 v[56:59], v[184:187], v[208:211], v[56:59]
	v_mfma_f32_16x16x32_bf16 v[44:47], v[176:179], v[216:219], v[44:47]
	v_mfma_f32_16x16x32_bf16 v[40:43], v[184:187], v[216:219], v[40:43]
	v_mfma_f32_16x16x32_bf16 v[28:31], v[176:179], v[224:227], v[28:31]
	v_mfma_f32_16x16x32_bf16 v[24:27], v[184:187], v[224:227], v[24:27]
	v_mfma_f32_16x16x32_bf16 v[12:15], v[176:179], v[232:235], v[12:15]
	v_mfma_f32_16x16x32_bf16 v[8:11], v[184:187], v[232:235], v[8:11]
	s_setprio 0
	s_setprio 1
	v_mfma_f32_16x16x32_bf16 v[52:55], v[188:191], v[204:207], v[52:55]
	v_mfma_f32_16x16x32_bf16 v[48:51], v[196:199], v[204:207], v[48:51]
	v_mfma_f32_16x16x32_bf16 v[36:39], v[188:191], v[212:215], v[36:39]
	v_mfma_f32_16x16x32_bf16 v[32:35], v[196:199], v[212:215], v[32:35]
	v_mfma_f32_16x16x32_bf16 v[20:23], v[188:191], v[220:223], v[20:23]
	v_mfma_f32_16x16x32_bf16 v[16:19], v[196:199], v[220:223], v[16:19]
	v_mfma_f32_16x16x32_bf16 v[4:7], v[188:191], v[228:231], v[4:7]
	v_mfma_f32_16x16x32_bf16 v[0:3], v[196:199], v[228:231], v[0:3]
	s_setprio 0
	s_setprio 1
	v_mfma_f32_16x16x32_bf16 v[52:55], v[192:195], v[208:211], v[52:55]
	v_mfma_f32_16x16x32_bf16 v[48:51], v[200:203], v[208:211], v[48:51]
	v_mfma_f32_16x16x32_bf16 v[36:39], v[192:195], v[216:219], v[36:39]
	v_mfma_f32_16x16x32_bf16 v[32:35], v[200:203], v[216:219], v[32:35]
	v_mfma_f32_16x16x32_bf16 v[20:23], v[192:195], v[224:227], v[20:23]
	v_mfma_f32_16x16x32_bf16 v[16:19], v[200:203], v[224:227], v[16:19]
	v_mfma_f32_16x16x32_bf16 v[4:7], v[192:195], v[232:235], v[4:7]
	v_mfma_f32_16x16x32_bf16 v[0:3], v[200:203], v[232:235], v[0:3]
	s_setprio 0
	s_barrier
	s_add_i32 s63, s63, 2
	s_add_u32 s61, s61, 0x100
	s_addc_u32 s62, s62, 0
	s_add_u32 s8, s8, 0x10000
	s_addc_u32 s9, s9, 0
	s_cmp_gt_u32 s63, 13
	s_cbranch_scc0 .LBB0_534
